# v12 plus prefetch of the 16 W_ada loads per iteration in the adaLN GEMV of the prep phase (counted vmcnt)
# speedup vs baseline: 1.0243x; 1.0051x over previous
; DI void prep_mod_item(const Params& p, int item, float* smem) {
;     ...
;     __syncthreads();
;     const float* Wh = W + (size_t)(half * 512 + wv * 64) * 3072 + col;
;     const float* sg = smem + wv * 64;
; #pragma unroll 16
;     for (int kk = 0; kk < 64; ++kk) {
;       const float w = Wh[(size_t)kk * 3072];
; #pragma unroll
;       for (int b = 0; b < 33; ++b) acc[b] += sg[b * 512 + kk] * w;
;     }
.LBB0_66:
	s_or_b64 exec, exec, s[0:1]
	v_add_u32_e32 v0, s2, v190
	s_xor_b64 s[0:1], s[8:9], -1
	v_mad_i64_i32 v[150:151], s[8:9], v0, s3, v[148:149]
	s_mov_b32 s8, 0
	s_waitcnt lgkmcnt(0)
	s_barrier
	s_movk_i32 s100, 0x3000
	s_mov_b32 s101, 0
.LBB0_67:
	s_mul_i32 s78, s8, 0xc00
	v_lshl_add_u64 v[160:161], s[78:79], 2, v[150:151]
	global_load_dword v225, v[160:161], off
	v_lshl_add_u64 v[242:243], v[160:161], 0, s[100:101]
	global_load_dword v226, v[242:243], off
	v_lshl_add_u64 v[242:243], v[242:243], 0, s[100:101]
	global_load_dword v227, v[242:243], off
	v_lshl_add_u64 v[242:243], v[242:243], 0, s[100:101]
	global_load_dword v228, v[242:243], off
	v_lshl_add_u64 v[242:243], v[242:243], 0, s[100:101]
	global_load_dword v229, v[242:243], off
	v_lshl_add_u64 v[242:243], v[242:243], 0, s[100:101]
	global_load_dword v230, v[242:243], off
	v_lshl_add_u64 v[242:243], v[242:243], 0, s[100:101]
	global_load_dword v231, v[242:243], off
	v_lshl_add_u64 v[242:243], v[242:243], 0, s[100:101]
	global_load_dword v232, v[242:243], off
	v_lshl_add_u64 v[242:243], v[242:243], 0, s[100:101]
	global_load_dword v233, v[242:243], off
	v_lshl_add_u64 v[242:243], v[242:243], 0, s[100:101]
	global_load_dword v234, v[242:243], off
	v_lshl_add_u64 v[242:243], v[242:243], 0, s[100:101]
	global_load_dword v235, v[242:243], off
	v_lshl_add_u64 v[242:243], v[242:243], 0, s[100:101]
	global_load_dword v236, v[242:243], off
	v_lshl_add_u64 v[242:243], v[242:243], 0, s[100:101]
	global_load_dword v237, v[242:243], off
	v_lshl_add_u64 v[242:243], v[242:243], 0, s[100:101]
	global_load_dword v238, v[242:243], off
	v_lshl_add_u64 v[242:243], v[242:243], 0, s[100:101]
	global_load_dword v239, v[242:243], off
	v_lshl_add_u64 v[242:243], v[242:243], 0, s[100:101]
	global_load_dword v240, v[242:243], off
	v_lshl_add_u32 v195, s8, 2, v192
	ds_read_b128 v[46:49], v195
	ds_read_b128 v[10:13], v195 offset:16
	ds_read_b128 v[6:9], v195 offset:32
	ds_read_b128 v[2:5], v195 offset:48
	ds_read_b128 v[50:53], v195 offset:2048
	ds_read_b128 v[54:57], v195 offset:4096
	v_add_co_u32_e32 v160, vcc, s3, v160
	s_or_b32 s2, s8, 2
	s_waitcnt lgkmcnt(1)
	v_mov_b32_e32 v59, v50
	s_waitcnt lgkmcnt(0)
	v_mov_b32_e32 v58, v54
	v_addc_co_u32_e32 v161, vcc, 0, v161, vcc
	s_mul_i32 s78, s2, 0xc00
	v_mov_b32_e32 v50, v55
	s_or_b32 s2, s8, 3
	s_waitcnt vmcnt(15)
	v_mov_b32_e32 v0, v225
	v_pk_fma_f32 v[162:163], v[0:1], v[58:59], v[14:15] op_sel_hi:[0,1,1]
	ds_read_b128 v[58:61], v195 offset:6144
	ds_read_b128 v[62:65], v195 offset:8192
	v_fmac_f32_e32 v191, v0, v46
	s_waitcnt lgkmcnt(1)
	v_mov_b32_e32 v15, v58
	s_waitcnt lgkmcnt(0)
	v_mov_b32_e32 v14, v62
	v_pk_fma_f32 v[164:165], v[0:1], v[14:15], v[16:17] op_sel_hi:[0,1,1]
	ds_read_b128 v[14:17], v195 offset:10240
	ds_read_b128 v[66:69], v195 offset:12288
	v_mov_b32_e32 v58, v63
	s_waitcnt lgkmcnt(1)
	v_mov_b32_e32 v71, v14
	s_waitcnt lgkmcnt(0)
	v_mov_b32_e32 v70, v66
	v_pk_fma_f32 v[166:167], v[0:1], v[70:71], v[18:19] op_sel_hi:[0,1,1]
	ds_read_b128 v[70:73], v195 offset:14336
	ds_read_b128 v[74:77], v195 offset:16384
	v_add_u32_e32 v14, 0x10000, v195
	s_waitcnt lgkmcnt(1)
	v_mov_b32_e32 v19, v70
	s_waitcnt lgkmcnt(0)
	v_mov_b32_e32 v18, v74
	v_pk_fma_f32 v[168:169], v[0:1], v[18:19], v[20:21] op_sel_hi:[0,1,1]
	ds_read_b128 v[18:21], v195 offset:18432
	ds_read_b128 v[78:81], v195 offset:20480
	v_mov_b32_e32 v70, v75
	s_waitcnt lgkmcnt(1)
	v_mov_b32_e32 v83, v18
	s_waitcnt lgkmcnt(0)
	v_mov_b32_e32 v82, v78
	v_pk_fma_f32 v[170:171], v[0:1], v[82:83], v[22:23] op_sel_hi:[0,1,1]
	ds_read_b128 v[82:85], v195 offset:22528
	ds_read_b128 v[86:89], v195 offset:24576
	ds_read_b128 v[90:93], v195 offset:26624
	ds_read_b128 v[94:97], v195 offset:28672
	ds_read_b128 v[98:101], v195 offset:30720
	ds_read_b128 v[102:105], v195 offset:32768
	v_mov_b32_e32 v18, v79
	s_waitcnt lgkmcnt(5)
	v_mov_b32_e32 v23, v82
	s_waitcnt lgkmcnt(4)
	v_mov_b32_e32 v22, v86
	v_pk_fma_f32 v[172:173], v[0:1], v[22:23], v[26:27] op_sel_hi:[0,1,1]
	s_waitcnt lgkmcnt(2)
	v_mov_b32_e32 v22, v94
	v_mov_b32_e32 v23, v90
	v_pk_fma_f32 v[174:175], v[0:1], v[22:23], v[30:31] op_sel_hi:[0,1,1]
	s_waitcnt lgkmcnt(0)
	v_mov_b32_e32 v22, v102
	v_mov_b32_e32 v23, v98
	v_pk_fma_f32 v[176:177], v[0:1], v[22:23], v[24:25] op_sel_hi:[0,1,1]
	ds_read_b128 v[22:25], v195 offset:34816
	ds_read_b128 v[106:109], v195 offset:36864
	v_mov_b32_e32 v82, v87
	v_mov_b32_e32 v90, v95
	v_mov_b32_e32 v98, v103
	s_waitcnt lgkmcnt(1)
	v_mov_b32_e32 v27, v22
	s_waitcnt lgkmcnt(0)
	v_mov_b32_e32 v26, v106
	v_pk_fma_f32 v[178:179], v[0:1], v[26:27], v[28:29] op_sel_hi:[0,1,1]
	ds_read_b128 v[26:29], v195 offset:38912
	ds_read_b128 v[110:113], v195 offset:40960
	v_mov_b32_e32 v22, v107
	s_waitcnt lgkmcnt(1)
	v_mov_b32_e32 v31, v26
	s_waitcnt lgkmcnt(0)
	v_mov_b32_e32 v30, v110
	v_pk_fma_f32 v[180:181], v[0:1], v[30:31], v[32:33] op_sel_hi:[0,1,1]
	ds_read_b128 v[30:33], v195 offset:43008
	ds_read_b128 v[114:117], v195 offset:45056
	v_mov_b32_e32 v26, v111
	s_waitcnt lgkmcnt(1)
	v_mov_b32_e32 v119, v30
	s_waitcnt lgkmcnt(0)
	v_mov_b32_e32 v118, v114
	v_pk_fma_f32 v[182:183], v[0:1], v[118:119], v[34:35] op_sel_hi:[0,1,1]
	ds_read_b128 v[118:121], v195 offset:47104
	ds_read_b128 v[122:125], v195 offset:49152
	v_mov_b32_e32 v30, v115
	s_waitcnt lgkmcnt(1)
	v_mov_b32_e32 v35, v118
	s_waitcnt lgkmcnt(0)
	v_mov_b32_e32 v34, v122
	v_pk_fma_f32 v[184:185], v[0:1], v[34:35], v[36:37] op_sel_hi:[0,1,1]
	ds_read_b128 v[34:37], v195 offset:51200
	ds_read_b128 v[126:129], v195 offset:53248
	v_mov_b32_e32 v118, v123
	s_waitcnt lgkmcnt(1)
	v_mov_b32_e32 v131, v34
	s_waitcnt lgkmcnt(0)
; DI void prep_mod_item(const Params& p, int item, float* smem) {
;     ...
; #pragma unroll 16
;     for (int kk = 0; kk < 64; ++kk) {
;       const float w = Wh[(size_t)kk * 3072];
; #pragma unroll
;       for (int b = 0; b < 33; ++b) acc[b] += sg[b * 512 + kk] * w;
;     }
	v_mov_b32_e32 v130, v126
	v_pk_fma_f32 v[186:187], v[0:1], v[130:131], v[38:39] op_sel_hi:[0,1,1]
	ds_read_b128 v[130:133], v195 offset:55296
	ds_read_b128 v[134:137], v195 offset:57344
	v_mov_b32_e32 v34, v127
	s_waitcnt lgkmcnt(1)
	v_mov_b32_e32 v39, v130
	s_waitcnt lgkmcnt(0)
	v_mov_b32_e32 v38, v134
	v_pk_fma_f32 v[196:197], v[0:1], v[38:39], v[40:41] op_sel_hi:[0,1,1]
	ds_read_b128 v[38:41], v195 offset:59392
	ds_read_b128 v[138:141], v195 offset:61440
	ds_read_b128 v[156:159], v14
	v_mov_b32_e32 v14, v67
	v_mov_b32_e32 v130, v135
	s_waitcnt lgkmcnt(2)
	v_mov_b32_e32 v153, v38
	s_waitcnt lgkmcnt(1)
	v_mov_b32_e32 v152, v138
	v_pk_fma_f32 v[42:43], v[0:1], v[152:153], v[42:43] op_sel_hi:[0,1,1]
	ds_read_b128 v[152:155], v195 offset:63488
	s_waitcnt lgkmcnt(1)
	v_mov_b32_e32 v198, v156
	v_mov_b32_e32 v38, v139
	s_waitcnt lgkmcnt(0)
	v_mov_b32_e32 v199, v152
	v_pk_fma_f32 v[44:45], v[0:1], v[198:199], v[44:45] op_sel_hi:[0,1,1]
	s_nop 0
	v_mov_b32_e32 v152, v157
	s_waitcnt vmcnt(14)
	v_mov_b32_e32 v0, v226
	v_pk_fma_f32 v[38:39], v[0:1], v[38:39], v[42:43] op_sel_hi:[0,1,1]
	v_pk_fma_f32 v[42:43], v[0:1], v[152:153], v[44:45] op_sel_hi:[0,1,1]
	v_lshl_add_u64 v[44:45], s[78:79], 2, v[150:151]
	v_fmac_f32_e32 v191, v0, v47
	v_pk_fma_f32 v[46:47], v[0:1], v[50:51], v[162:163] op_sel_hi:[0,1,1]
	v_pk_fma_f32 v[50:51], v[0:1], v[58:59], v[164:165] op_sel_hi:[0,1,1]
	v_pk_fma_f32 v[14:15], v[0:1], v[14:15], v[166:167] op_sel_hi:[0,1,1]
	v_pk_fma_f32 v[54:55], v[0:1], v[70:71], v[168:169] op_sel_hi:[0,1,1]
	v_pk_fma_f32 v[18:19], v[0:1], v[18:19], v[170:171] op_sel_hi:[0,1,1]
	v_pk_fma_f32 v[58:59], v[0:1], v[82:83], v[172:173] op_sel_hi:[0,1,1]
	v_pk_fma_f32 v[62:63], v[0:1], v[90:91], v[174:175] op_sel_hi:[0,1,1]
	v_pk_fma_f32 v[66:67], v[0:1], v[98:99], v[176:177] op_sel_hi:[0,1,1]
	v_pk_fma_f32 v[22:23], v[0:1], v[22:23], v[178:179] op_sel_hi:[0,1,1]
	v_pk_fma_f32 v[26:27], v[0:1], v[26:27], v[180:181] op_sel_hi:[0,1,1]
	v_pk_fma_f32 v[30:31], v[0:1], v[30:31], v[182:183] op_sel_hi:[0,1,1]
	v_pk_fma_f32 v[70:71], v[0:1], v[118:119], v[184:185] op_sel_hi:[0,1,1]
	v_pk_fma_f32 v[34:35], v[0:1], v[34:35], v[186:187] op_sel_hi:[0,1,1]
	v_pk_fma_f32 v[74:75], v[0:1], v[130:131], v[196:197] op_sel_hi:[0,1,1]
	s_nop 0
	v_mov_b32_e32 v44, v56
	v_mov_b32_e32 v45, v52
	s_mul_i32 s78, s2, 0xc00
	s_or_b32 s2, s8, 4
	v_mov_b32_e32 v52, v57
	s_waitcnt vmcnt(13)
	v_mov_b32_e32 v0, v227
	v_pk_fma_f32 v[44:45], v[0:1], v[44:45], v[46:47] op_sel_hi:[0,1,1]
	v_mov_b32_e32 v46, v64
	v_mov_b32_e32 v47, v60
	v_pk_fma_f32 v[46:47], v[0:1], v[46:47], v[50:51] op_sel_hi:[0,1,1]
	v_mov_b32_e32 v50, v68
	v_mov_b32_e32 v51, v16
	v_pk_fma_f32 v[14:15], v[0:1], v[50:51], v[14:15] op_sel_hi:[0,1,1]
	v_mov_b32_e32 v50, v76
	v_mov_b32_e32 v51, v72
	v_pk_fma_f32 v[50:51], v[0:1], v[50:51], v[54:55] op_sel_hi:[0,1,1]
	v_mov_b32_e32 v54, v80
	v_mov_b32_e32 v55, v20
	v_pk_fma_f32 v[18:19], v[0:1], v[54:55], v[18:19] op_sel_hi:[0,1,1]
	v_mov_b32_e32 v54, v88
	v_mov_b32_e32 v55, v84
	v_pk_fma_f32 v[58:59], v[0:1], v[54:55], v[58:59] op_sel_hi:[0,1,1]
	v_mov_b32_e32 v54, v96
	v_mov_b32_e32 v55, v92
	v_pk_fma_f32 v[62:63], v[0:1], v[54:55], v[62:63] op_sel_hi:[0,1,1]
	v_mov_b32_e32 v54, v104
	v_mov_b32_e32 v55, v100
	v_pk_fma_f32 v[66:67], v[0:1], v[54:55], v[66:67] op_sel_hi:[0,1,1]
	v_mov_b32_e32 v54, v108
	v_mov_b32_e32 v55, v24
	v_pk_fma_f32 v[78:79], v[0:1], v[54:55], v[22:23] op_sel_hi:[0,1,1]
	v_mov_b32_e32 v22, v112
	v_mov_b32_e32 v23, v28
	v_pk_fma_f32 v[26:27], v[0:1], v[22:23], v[26:27] op_sel_hi:[0,1,1]
	v_mov_b32_e32 v22, v116
	v_mov_b32_e32 v23, v32
	v_pk_fma_f32 v[86:87], v[0:1], v[22:23], v[30:31] op_sel_hi:[0,1,1]
	v_mov_b32_e32 v22, v124
	v_mov_b32_e32 v23, v120
	v_pk_fma_f32 v[70:71], v[0:1], v[22:23], v[70:71] op_sel_hi:[0,1,1]
	v_mov_b32_e32 v22, v128
	v_mov_b32_e32 v23, v36
	v_pk_fma_f32 v[34:35], v[0:1], v[22:23], v[34:35] op_sel_hi:[0,1,1]
	v_mov_b32_e32 v22, v136
	v_mov_b32_e32 v23, v132
	v_pk_fma_f32 v[94:95], v[0:1], v[22:23], v[74:75] op_sel_hi:[0,1,1]
	v_mov_b32_e32 v22, v140
	v_mov_b32_e32 v23, v40
	v_pk_fma_f32 v[102:103], v[0:1], v[22:23], v[38:39] op_sel_hi:[0,1,1]
	v_mov_b32_e32 v22, v158
	v_mov_b32_e32 v23, v154
	v_pk_fma_f32 v[42:43], v[0:1], v[22:23], v[42:43] op_sel_hi:[0,1,1]
	v_lshl_add_u64 v[22:23], s[78:79], 2, v[150:151]
	v_fmac_f32_e32 v191, v0, v48
	s_nop 0
	v_mov_b32_e32 v16, v69
	s_mul_i32 s78, s2, 0xc00
	v_mov_b32_e32 v60, v65
	v_mov_b32_e32 v72, v77
	v_mov_b32_e32 v20, v81
	v_mov_b32_e32 v84, v89
	v_mov_b32_e32 v92, v97
	v_mov_b32_e32 v100, v105
	v_mov_b32_e32 v24, v109
	v_mov_b32_e32 v28, v113
	v_mov_b32_e32 v32, v117
	v_mov_b32_e32 v120, v125
	v_mov_b32_e32 v36, v129
	v_mov_b32_e32 v132, v137
	v_mov_b32_e32 v40, v141
	v_mov_b32_e32 v154, v159
	s_or_b32 s2, s8, 5
	s_waitcnt vmcnt(12)
	v_mov_b32_e32 v0, v228
	v_pk_fma_f32 v[38:39], v[0:1], v[16:17], v[14:15] op_sel_hi:[0,1,1]
	v_lshl_add_u64 v[14:15], s[78:79], 2, v[150:151]
	v_fmac_f32_e32 v191, v0, v49
	v_pk_fma_f32 v[22:23], v[0:1], v[52:53], v[44:45] op_sel_hi:[0,1,1]
	v_pk_fma_f32 v[30:31], v[0:1], v[60:61], v[46:47] op_sel_hi:[0,1,1]
	v_pk_fma_f32 v[46:47], v[0:1], v[72:73], v[50:51] op_sel_hi:[0,1,1]
	v_pk_fma_f32 v[54:55], v[0:1], v[20:21], v[18:19] op_sel_hi:[0,1,1]
	v_pk_fma_f32 v[64:65], v[0:1], v[84:85], v[58:59] op_sel_hi:[0,1,1]
	v_pk_fma_f32 v[62:63], v[0:1], v[92:93], v[62:63] op_sel_hi:[0,1,1]
	v_pk_fma_f32 v[74:75], v[0:1], v[100:101], v[66:67] op_sel_hi:[0,1,1]
	v_pk_fma_f32 v[82:83], v[0:1], v[24:25], v[78:79] op_sel_hi:[0,1,1]
	v_pk_fma_f32 v[90:91], v[0:1], v[28:29], v[26:27] op_sel_hi:[0,1,1]
	v_pk_fma_f32 v[98:99], v[0:1], v[32:33], v[86:87] op_sel_hi:[0,1,1]
	v_pk_fma_f32 v[106:107], v[0:1], v[120:121], v[70:71] op_sel_hi:[0,1,1]
	v_pk_fma_f32 v[114:115], v[0:1], v[36:37], v[34:35] op_sel_hi:[0,1,1]
	v_pk_fma_f32 v[122:123], v[0:1], v[132:133], v[94:95] op_sel_hi:[0,1,1]
	v_pk_fma_f32 v[134:135], v[0:1], v[40:41], v[102:103] op_sel_hi:[0,1,1]
	v_pk_fma_f32 v[176:177], v[0:1], v[154:155], v[42:43] op_sel_hi:[0,1,1]
	s_nop 0
	ds_read_b128 v[14:17], v195 offset:2064
	ds_read_b128 v[18:21], v195 offset:4112
	s_mul_i32 s78, s2, 0xc00
	s_or_b32 s2, s8, 6
	s_waitcnt lgkmcnt(1)
; DI void prep_mod_item(const Params& p, int item, float* smem) {
;     ...
; #pragma unroll 16
;     for (int kk = 0; kk < 64; ++kk) {
;       const float w = Wh[(size_t)kk * 3072];
; #pragma unroll
;       for (int b = 0; b < 33; ++b) acc[b] += sg[b * 512 + kk] * w;
;     }
	v_mov_b32_e32 v25, v14
	s_waitcnt lgkmcnt(0)
	v_mov_b32_e32 v24, v18
	v_mov_b32_e32 v14, v19
	s_waitcnt vmcnt(11)
	v_mov_b32_e32 v0, v229
	v_pk_fma_f32 v[152:153], v[0:1], v[24:25], v[22:23] op_sel_hi:[0,1,1]
	ds_read_b128 v[22:25], v195 offset:6160
	ds_read_b128 v[26:29], v195 offset:8208
	v_fmac_f32_e32 v191, v0, v10
	v_add_u32_e32 v10, 0x10010, v195
	s_waitcnt lgkmcnt(1)
	v_mov_b32_e32 v33, v22
	s_waitcnt lgkmcnt(0)
	v_mov_b32_e32 v32, v26
	v_pk_fma_f32 v[154:155], v[0:1], v[32:33], v[30:31] op_sel_hi:[0,1,1]
	ds_read_b128 v[30:33], v195 offset:10256
	ds_read_b128 v[34:37], v195 offset:12304
	v_mov_b32_e32 v22, v27
	s_waitcnt lgkmcnt(1)
	v_mov_b32_e32 v41, v30
	s_waitcnt lgkmcnt(0)
	v_mov_b32_e32 v40, v34
	v_pk_fma_f32 v[156:157], v[0:1], v[40:41], v[38:39] op_sel_hi:[0,1,1]
	ds_read_b128 v[38:41], v195 offset:14352
	ds_read_b128 v[42:45], v195 offset:16400
	v_mov_b32_e32 v30, v35
	s_waitcnt lgkmcnt(1)
	v_mov_b32_e32 v49, v38
	s_waitcnt lgkmcnt(0)
	v_mov_b32_e32 v48, v42
	v_pk_fma_f32 v[158:159], v[0:1], v[48:49], v[46:47] op_sel_hi:[0,1,1]
	ds_read_b128 v[46:49], v195 offset:18448
	ds_read_b128 v[50:53], v195 offset:20496
	v_mov_b32_e32 v38, v43
	s_waitcnt lgkmcnt(1)
	v_mov_b32_e32 v57, v46
	s_waitcnt lgkmcnt(0)
	v_mov_b32_e32 v56, v50
	v_pk_fma_f32 v[160:161], v[0:1], v[56:57], v[54:55] op_sel_hi:[0,1,1]
	ds_read_b128 v[54:57], v195 offset:22544
	ds_read_b128 v[58:61], v195 offset:24592
	v_mov_b32_e32 v46, v51
	s_waitcnt lgkmcnt(1)
	v_mov_b32_e32 v67, v54
	s_waitcnt lgkmcnt(0)
	v_mov_b32_e32 v66, v58
	v_pk_fma_f32 v[162:163], v[0:1], v[66:67], v[64:65] op_sel_hi:[0,1,1]
	ds_read_b128 v[66:69], v195 offset:26640
	ds_read_b128 v[70:73], v195 offset:28688
	v_mov_b32_e32 v54, v59
	s_waitcnt lgkmcnt(1)
	v_mov_b32_e32 v65, v66
	s_waitcnt lgkmcnt(0)
	v_mov_b32_e32 v64, v70
	v_pk_fma_f32 v[164:165], v[0:1], v[64:65], v[62:63] op_sel_hi:[0,1,1]
	ds_read_b128 v[62:65], v195 offset:30736
	ds_read_b128 v[78:81], v195 offset:32784
	v_mov_b32_e32 v66, v71
	s_waitcnt lgkmcnt(1)
	v_mov_b32_e32 v77, v62
	s_waitcnt lgkmcnt(0)
	v_mov_b32_e32 v76, v78
	v_pk_fma_f32 v[166:167], v[0:1], v[76:77], v[74:75] op_sel_hi:[0,1,1]
	ds_read_b128 v[74:77], v195 offset:34832
	ds_read_b128 v[86:89], v195 offset:36880
	v_mov_b32_e32 v62, v79
	s_waitcnt lgkmcnt(1)
	v_mov_b32_e32 v85, v74
	s_waitcnt lgkmcnt(0)
	v_mov_b32_e32 v84, v86
	v_pk_fma_f32 v[168:169], v[0:1], v[84:85], v[82:83] op_sel_hi:[0,1,1]
	ds_read_b128 v[82:85], v195 offset:38928
	ds_read_b128 v[94:97], v195 offset:40976
	v_mov_b32_e32 v74, v87
	s_waitcnt lgkmcnt(1)
	v_mov_b32_e32 v93, v82
	s_waitcnt lgkmcnt(0)
	v_mov_b32_e32 v92, v94
	v_pk_fma_f32 v[170:171], v[0:1], v[92:93], v[90:91] op_sel_hi:[0,1,1]
	ds_read_b128 v[90:93], v195 offset:43024
	ds_read_b128 v[102:105], v195 offset:45072
	v_mov_b32_e32 v82, v95
	s_waitcnt lgkmcnt(1)
	v_mov_b32_e32 v101, v90
	s_waitcnt lgkmcnt(0)
	v_mov_b32_e32 v100, v102
	v_pk_fma_f32 v[172:173], v[0:1], v[100:101], v[98:99] op_sel_hi:[0,1,1]
	ds_read_b128 v[98:101], v195 offset:47120
	ds_read_b128 v[110:113], v195 offset:49168
	v_mov_b32_e32 v90, v103
	s_waitcnt lgkmcnt(1)
	v_mov_b32_e32 v109, v98
	s_waitcnt lgkmcnt(0)
	v_mov_b32_e32 v108, v110
	v_pk_fma_f32 v[174:175], v[0:1], v[108:109], v[106:107] op_sel_hi:[0,1,1]
	ds_read_b128 v[106:109], v195 offset:51216
	ds_read_b128 v[118:121], v195 offset:53264
	v_mov_b32_e32 v98, v111
	s_waitcnt lgkmcnt(1)
	v_mov_b32_e32 v117, v106
	s_waitcnt lgkmcnt(0)
	v_mov_b32_e32 v116, v118
	v_pk_fma_f32 v[178:179], v[0:1], v[116:117], v[114:115] op_sel_hi:[0,1,1]
	ds_read_b128 v[114:117], v195 offset:55312
	ds_read_b128 v[126:129], v195 offset:57360
	v_mov_b32_e32 v106, v119
	s_waitcnt lgkmcnt(1)
	v_mov_b32_e32 v125, v114
	s_waitcnt lgkmcnt(0)
	v_mov_b32_e32 v124, v126
	v_pk_fma_f32 v[180:181], v[0:1], v[124:125], v[122:123] op_sel_hi:[0,1,1]
	ds_read_b128 v[122:125], v195 offset:59408
	ds_read_b128 v[130:133], v195 offset:61456
	ds_read_b128 v[138:141], v10
	v_mov_b32_e32 v114, v127
	s_waitcnt lgkmcnt(2)
	v_mov_b32_e32 v137, v122
	s_waitcnt lgkmcnt(1)
	v_mov_b32_e32 v136, v130
	v_pk_fma_f32 v[182:183], v[0:1], v[136:137], v[134:135] op_sel_hi:[0,1,1]
	ds_read_b128 v[134:137], v195 offset:63504
	s_waitcnt lgkmcnt(1)
	v_mov_b32_e32 v184, v138
	v_mov_b32_e32 v122, v131
	s_waitcnt lgkmcnt(0)
	v_mov_b32_e32 v185, v134
	v_pk_fma_f32 v[176:177], v[0:1], v[184:185], v[176:177] op_sel_hi:[0,1,1]
	v_lshl_add_u64 v[184:185], s[78:79], 2, v[150:151]
	s_nop 0
	s_mul_i32 s78, s2, 0xc00
	v_mov_b32_e32 v134, v139
	s_or_b32 s2, s8, 7
	s_waitcnt vmcnt(10)
	v_mov_b32_e32 v0, v230
	v_pk_fma_f32 v[50:51], v[0:1], v[54:55], v[162:163] op_sel_hi:[0,1,1]
	v_lshl_add_u64 v[54:55], s[78:79], 2, v[150:151]
	v_fmac_f32_e32 v191, v0, v11
	v_pk_fma_f32 v[186:187], v[0:1], v[14:15], v[152:153] op_sel_hi:[0,1,1]
	v_pk_fma_f32 v[184:185], v[0:1], v[22:23], v[154:155] op_sel_hi:[0,1,1]
	v_pk_fma_f32 v[156:157], v[0:1], v[30:31], v[156:157] op_sel_hi:[0,1,1]
	v_pk_fma_f32 v[154:155], v[0:1], v[38:39], v[158:159] op_sel_hi:[0,1,1]
	v_pk_fma_f32 v[152:153], v[0:1], v[46:47], v[160:161] op_sel_hi:[0,1,1]
	v_pk_fma_f32 v[38:39], v[0:1], v[66:67], v[164:165] op_sel_hi:[0,1,1]
	v_pk_fma_f32 v[30:31], v[0:1], v[62:63], v[166:167] op_sel_hi:[0,1,1]
	v_pk_fma_f32 v[46:47], v[0:1], v[74:75], v[168:169] op_sel_hi:[0,1,1]
	v_pk_fma_f32 v[34:35], v[0:1], v[82:83], v[170:171] op_sel_hi:[0,1,1]
	v_pk_fma_f32 v[42:43], v[0:1], v[90:91], v[172:173] op_sel_hi:[0,1,1]
	v_pk_fma_f32 v[26:27], v[0:1], v[98:99], v[174:175] op_sel_hi:[0,1,1]
	v_pk_fma_f32 v[22:23], v[0:1], v[106:107], v[178:179] op_sel_hi:[0,1,1]
	v_pk_fma_f32 v[18:19], v[0:1], v[114:115], v[180:181] op_sel_hi:[0,1,1]
	v_pk_fma_f32 v[14:15], v[0:1], v[122:123], v[182:183] op_sel_hi:[0,1,1]
	v_pk_fma_f32 v[10:11], v[0:1], v[134:135], v[176:177] op_sel_hi:[0,1,1]
	s_nop 0
	v_mov_b32_e32 v62, v52
	v_mov_b32_e32 v63, v48
	v_mov_b32_e32 v54, v20
	v_mov_b32_e32 v55, v16
	s_mul_i32 s78, s2, 0xc00
	s_or_b32 s2, s8, 8
	v_mov_b32_e32 v48, v53
	v_mov_b32_e32 v16, v21
	s_waitcnt vmcnt(9)
; DI void prep_mod_item(const Params& p, int item, float* smem) {
;     ...
; #pragma unroll 16
;     for (int kk = 0; kk < 64; ++kk) {
;       const float w = Wh[(size_t)kk * 3072];
; #pragma unroll
;       for (int b = 0; b < 33; ++b) acc[b] += sg[b * 512 + kk] * w;
;     }
	v_mov_b32_e32 v0, v231
	v_pk_fma_f32 v[70:71], v[0:1], v[62:63], v[152:153] op_sel_hi:[0,1,1]
	v_mov_b32_e32 v62, v60
	v_mov_b32_e32 v63, v56
	v_pk_fma_f32 v[50:51], v[0:1], v[62:63], v[50:51] op_sel_hi:[0,1,1]
	v_mov_b32_e32 v62, v72
	v_mov_b32_e32 v63, v68
	v_pk_fma_f32 v[38:39], v[0:1], v[62:63], v[38:39] op_sel_hi:[0,1,1]
	v_mov_b32_e32 v62, v80
	v_mov_b32_e32 v63, v64
	v_pk_fma_f32 v[30:31], v[0:1], v[62:63], v[30:31] op_sel_hi:[0,1,1]
	v_mov_b32_e32 v62, v88
	v_mov_b32_e32 v63, v76
	v_pk_fma_f32 v[66:67], v[0:1], v[62:63], v[46:47] op_sel_hi:[0,1,1]
	v_mov_b32_e32 v46, v96
	v_mov_b32_e32 v47, v84
	v_pk_fma_f32 v[34:35], v[0:1], v[46:47], v[34:35] op_sel_hi:[0,1,1]
	v_mov_b32_e32 v46, v104
	v_mov_b32_e32 v47, v92
	v_pk_fma_f32 v[62:63], v[0:1], v[46:47], v[42:43] op_sel_hi:[0,1,1]
	v_mov_b32_e32 v42, v112
	v_mov_b32_e32 v43, v100
	v_pk_fma_f32 v[46:47], v[0:1], v[42:43], v[26:27] op_sel_hi:[0,1,1]
	v_mov_b32_e32 v26, v120
	v_mov_b32_e32 v27, v108
	v_pk_fma_f32 v[42:43], v[0:1], v[26:27], v[22:23] op_sel_hi:[0,1,1]
	v_mov_b32_e32 v22, v128
	v_mov_b32_e32 v23, v116
	v_pk_fma_f32 v[78:79], v[0:1], v[54:55], v[186:187] op_sel_hi:[0,1,1]
	v_mov_b32_e32 v54, v28
	v_mov_b32_e32 v55, v24
	v_pk_fma_f32 v[22:23], v[0:1], v[22:23], v[18:19] op_sel_hi:[0,1,1]
	v_mov_b32_e32 v18, v132
	v_mov_b32_e32 v19, v124
	v_pk_fma_f32 v[74:75], v[0:1], v[54:55], v[184:185] op_sel_hi:[0,1,1]
	v_mov_b32_e32 v54, v36
	v_mov_b32_e32 v55, v32
	v_pk_fma_f32 v[14:15], v[0:1], v[18:19], v[14:15] op_sel_hi:[0,1,1]
	v_mov_b32_e32 v18, v140
	v_mov_b32_e32 v19, v136
	v_pk_fma_f32 v[58:59], v[0:1], v[54:55], v[156:157] op_sel_hi:[0,1,1]
	v_mov_b32_e32 v54, v44
	v_mov_b32_e32 v55, v40
	v_pk_fma_f32 v[10:11], v[0:1], v[18:19], v[10:11] op_sel_hi:[0,1,1]
	v_lshl_add_u64 v[18:19], s[78:79], 2, v[150:151]
	v_fmac_f32_e32 v191, v0, v12
	v_pk_fma_f32 v[54:55], v[0:1], v[54:55], v[154:155] op_sel_hi:[0,1,1]
	s_nop 0
	v_mov_b32_e32 v136, v141
	s_mul_i32 s78, s2, 0xc00
	v_mov_b32_e32 v24, v29
	v_mov_b32_e32 v32, v37
	v_mov_b32_e32 v40, v45
	v_mov_b32_e32 v56, v61
	v_mov_b32_e32 v68, v73
	v_mov_b32_e32 v64, v81
	v_mov_b32_e32 v76, v89
	v_mov_b32_e32 v84, v97
	v_mov_b32_e32 v92, v105
	v_mov_b32_e32 v100, v113
	v_mov_b32_e32 v108, v121
	v_mov_b32_e32 v116, v129
	v_mov_b32_e32 v124, v133
	s_or_b32 s2, s8, 9
	s_waitcnt vmcnt(8)
	v_mov_b32_e32 v0, v232
	v_pk_fma_f32 v[52:53], v[0:1], v[48:49], v[70:71] op_sel_hi:[0,1,1]
	v_pk_fma_f32 v[48:49], v[0:1], v[136:137], v[10:11] op_sel_hi:[0,1,1]
	v_lshl_add_u64 v[10:11], s[78:79], 2, v[150:151]
	v_fmac_f32_e32 v191, v0, v13
	v_pk_fma_f32 v[18:19], v[0:1], v[16:17], v[78:79] op_sel_hi:[0,1,1]
	v_pk_fma_f32 v[26:27], v[0:1], v[24:25], v[74:75] op_sel_hi:[0,1,1]
	v_pk_fma_f32 v[58:59], v[0:1], v[32:33], v[58:59] op_sel_hi:[0,1,1]
	v_pk_fma_f32 v[54:55], v[0:1], v[40:41], v[54:55] op_sel_hi:[0,1,1]
	v_pk_fma_f32 v[50:51], v[0:1], v[56:57], v[50:51] op_sel_hi:[0,1,1]
	v_pk_fma_f32 v[38:39], v[0:1], v[68:69], v[38:39] op_sel_hi:[0,1,1]
	v_pk_fma_f32 v[30:31], v[0:1], v[64:65], v[30:31] op_sel_hi:[0,1,1]
	v_pk_fma_f32 v[32:33], v[0:1], v[76:77], v[66:67] op_sel_hi:[0,1,1]
	v_pk_fma_f32 v[34:35], v[0:1], v[84:85], v[34:35] op_sel_hi:[0,1,1]
	v_pk_fma_f32 v[36:37], v[0:1], v[92:93], v[62:63] op_sel_hi:[0,1,1]
	v_pk_fma_f32 v[40:41], v[0:1], v[100:101], v[46:47] op_sel_hi:[0,1,1]
	v_pk_fma_f32 v[42:43], v[0:1], v[108:109], v[42:43] op_sel_hi:[0,1,1]
	v_pk_fma_f32 v[44:45], v[0:1], v[116:117], v[22:23] op_sel_hi:[0,1,1]
	v_pk_fma_f32 v[46:47], v[0:1], v[124:125], v[14:15] op_sel_hi:[0,1,1]
	s_nop 0
	ds_read_b128 v[10:13], v195 offset:2080
	ds_read_b128 v[14:17], v195 offset:4128
	s_mul_i32 s78, s2, 0xc00
	s_or_b32 s2, s8, 10
	s_waitcnt lgkmcnt(1)
	v_mov_b32_e32 v21, v10
	s_waitcnt lgkmcnt(0)
	v_mov_b32_e32 v20, v14
	v_mov_b32_e32 v10, v15
	s_waitcnt vmcnt(7)
	v_mov_b32_e32 v0, v233
	v_pk_fma_f32 v[56:57], v[0:1], v[20:21], v[18:19] op_sel_hi:[0,1,1]
	ds_read_b128 v[18:21], v195 offset:6176
	ds_read_b128 v[22:25], v195 offset:8224
	v_fmac_f32_e32 v191, v0, v6
	v_add_u32_e32 v6, 0x10020, v195
	s_waitcnt lgkmcnt(1)
	v_mov_b32_e32 v29, v18
	s_waitcnt lgkmcnt(0)
	v_mov_b32_e32 v28, v22
	v_pk_fma_f32 v[140:141], v[0:1], v[28:29], v[26:27] op_sel_hi:[0,1,1]
	ds_read_b128 v[26:29], v195 offset:10272
	ds_read_b128 v[60:63], v195 offset:12320
	v_mov_b32_e32 v18, v23
	s_waitcnt lgkmcnt(1)
	v_mov_b32_e32 v65, v26
	s_waitcnt lgkmcnt(0)
	v_mov_b32_e32 v64, v60
	v_pk_fma_f32 v[58:59], v[0:1], v[64:65], v[58:59] op_sel_hi:[0,1,1]
	ds_read_b128 v[64:67], v195 offset:14368
	ds_read_b128 v[68:71], v195 offset:16416
	v_mov_b32_e32 v26, v61
	s_waitcnt lgkmcnt(1)
	v_mov_b32_e32 v73, v64
	s_waitcnt lgkmcnt(0)
	v_mov_b32_e32 v72, v68
	v_pk_fma_f32 v[160:161], v[0:1], v[72:73], v[54:55] op_sel_hi:[0,1,1]
	ds_read_b128 v[72:75], v195 offset:18464
	ds_read_b128 v[76:79], v195 offset:20512
	v_mov_b32_e32 v64, v69
	s_waitcnt lgkmcnt(1)
	v_mov_b32_e32 v55, v72
	s_waitcnt lgkmcnt(0)
	v_mov_b32_e32 v54, v76
	v_pk_fma_f32 v[162:163], v[0:1], v[54:55], v[52:53] op_sel_hi:[0,1,1]
	ds_read_b128 v[52:55], v195 offset:22560
	ds_read_b128 v[80:83], v195 offset:24608
	v_mov_b32_e32 v72, v77
	s_waitcnt lgkmcnt(1)
	v_mov_b32_e32 v85, v52
	s_waitcnt lgkmcnt(0)
	v_mov_b32_e32 v84, v80
	v_pk_fma_f32 v[50:51], v[0:1], v[84:85], v[50:51] op_sel_hi:[0,1,1]
	ds_read_b128 v[84:87], v195 offset:26656
	ds_read_b128 v[88:91], v195 offset:28704
	v_mov_b32_e32 v52, v81
	s_waitcnt lgkmcnt(1)
	v_mov_b32_e32 v93, v84
	s_waitcnt lgkmcnt(0)
	v_mov_b32_e32 v92, v88
	v_pk_fma_f32 v[164:165], v[0:1], v[92:93], v[38:39] op_sel_hi:[0,1,1]
	ds_read_b128 v[92:95], v195 offset:30752
	ds_read_b128 v[96:99], v195 offset:32800
	ds_read_b128 v[100:103], v195 offset:34848
	ds_read_b128 v[104:107], v195 offset:36896
	v_mov_b32_e32 v84, v89
	s_waitcnt lgkmcnt(3)
; DI void prep_mod_item(const Params& p, int item, float* smem) {
;     ...
; #pragma unroll 16
;     for (int kk = 0; kk < 64; ++kk) {
;       const float w = Wh[(size_t)kk * 3072];
; #pragma unroll
;       for (int b = 0; b < 33; ++b) acc[b] += sg[b * 512 + kk] * w;
;     }
	v_mov_b32_e32 v39, v92
	s_waitcnt lgkmcnt(2)
	v_mov_b32_e32 v38, v96
	v_pk_fma_f32 v[166:167], v[0:1], v[38:39], v[30:31] op_sel_hi:[0,1,1]
	s_waitcnt lgkmcnt(0)
	v_mov_b32_e32 v30, v104
	v_mov_b32_e32 v31, v100
	v_pk_fma_f32 v[168:169], v[0:1], v[30:31], v[32:33] op_sel_hi:[0,1,1]
	ds_read_b128 v[30:33], v195 offset:38944
	ds_read_b128 v[108:111], v195 offset:40992
	ds_read_b128 v[112:115], v195 offset:43040
	ds_read_b128 v[116:119], v195 offset:45088
	v_mov_b32_e32 v92, v97
	v_mov_b32_e32 v100, v105
	s_waitcnt lgkmcnt(3)
	v_mov_b32_e32 v39, v30
	s_waitcnt lgkmcnt(2)
	v_mov_b32_e32 v38, v108
	v_pk_fma_f32 v[170:171], v[0:1], v[38:39], v[34:35] op_sel_hi:[0,1,1]
	s_waitcnt lgkmcnt(0)
	v_mov_b32_e32 v34, v116
	v_mov_b32_e32 v35, v112
	v_pk_fma_f32 v[172:173], v[0:1], v[34:35], v[36:37] op_sel_hi:[0,1,1]
	ds_read_b128 v[34:37], v195 offset:47136
	ds_read_b128 v[120:123], v195 offset:49184
	v_mov_b32_e32 v30, v109
	v_mov_b32_e32 v112, v117
	s_waitcnt lgkmcnt(1)
	v_mov_b32_e32 v39, v34
	s_waitcnt lgkmcnt(0)
	v_mov_b32_e32 v38, v120
	v_pk_fma_f32 v[174:175], v[0:1], v[38:39], v[40:41] op_sel_hi:[0,1,1]
	ds_read_b128 v[38:41], v195 offset:51232
	ds_read_b128 v[124:127], v195 offset:53280
	v_mov_b32_e32 v34, v121
	s_waitcnt lgkmcnt(1)
	v_mov_b32_e32 v129, v38
	s_waitcnt lgkmcnt(0)
	v_mov_b32_e32 v128, v124
	v_pk_fma_f32 v[176:177], v[0:1], v[128:129], v[42:43] op_sel_hi:[0,1,1]
	ds_read_b128 v[128:131], v195 offset:55328
	ds_read_b128 v[132:135], v195 offset:57376
	v_mov_b32_e32 v38, v125
	s_waitcnt lgkmcnt(1)
	v_mov_b32_e32 v43, v128
	s_waitcnt lgkmcnt(0)
	v_mov_b32_e32 v42, v132
	v_pk_fma_f32 v[178:179], v[0:1], v[42:43], v[44:45] op_sel_hi:[0,1,1]
	ds_read_b128 v[42:45], v195 offset:59424
	ds_read_b128 v[136:139], v195 offset:61472
	ds_read_b128 v[156:159], v6
	v_mov_b32_e32 v128, v133
	s_waitcnt lgkmcnt(2)
	v_mov_b32_e32 v153, v42
	s_waitcnt lgkmcnt(1)
	v_mov_b32_e32 v152, v136
	v_pk_fma_f32 v[46:47], v[0:1], v[152:153], v[46:47] op_sel_hi:[0,1,1]
	ds_read_b128 v[152:155], v195 offset:63520
	s_waitcnt lgkmcnt(1)
	v_mov_b32_e32 v180, v156
	v_mov_b32_e32 v42, v137
	s_waitcnt lgkmcnt(0)
	v_mov_b32_e32 v181, v152
	v_pk_fma_f32 v[48:49], v[0:1], v[180:181], v[48:49] op_sel_hi:[0,1,1]
	v_lshl_add_u64 v[180:181], s[78:79], 2, v[150:151]
	s_nop 0
	v_mov_b32_e32 v152, v157
	s_mul_i32 s78, s2, 0xc00
	s_or_b32 s2, s8, 11
	s_waitcnt vmcnt(6)
	v_mov_b32_e32 v0, v234
	v_pk_fma_f32 v[42:43], v[0:1], v[42:43], v[46:47] op_sel_hi:[0,1,1]
	v_pk_fma_f32 v[46:47], v[0:1], v[152:153], v[48:49] op_sel_hi:[0,1,1]
	v_lshl_add_u64 v[48:49], s[78:79], 2, v[150:151]
	v_fmac_f32_e32 v191, v0, v7
	v_pk_fma_f32 v[6:7], v[0:1], v[10:11], v[56:57] op_sel_hi:[0,1,1]
	v_pk_fma_f32 v[10:11], v[0:1], v[18:19], v[140:141] op_sel_hi:[0,1,1]
	v_pk_fma_f32 v[14:15], v[0:1], v[26:27], v[58:59] op_sel_hi:[0,1,1]
	v_pk_fma_f32 v[18:19], v[0:1], v[64:65], v[160:161] op_sel_hi:[0,1,1]
	v_pk_fma_f32 v[22:23], v[0:1], v[72:73], v[162:163] op_sel_hi:[0,1,1]
	v_pk_fma_f32 v[26:27], v[0:1], v[52:53], v[50:51] op_sel_hi:[0,1,1]
	v_pk_fma_f32 v[50:51], v[0:1], v[84:85], v[164:165] op_sel_hi:[0,1,1]
	v_pk_fma_f32 v[52:53], v[0:1], v[92:93], v[166:167] op_sel_hi:[0,1,1]
	v_pk_fma_f32 v[56:57], v[0:1], v[100:101], v[168:169] op_sel_hi:[0,1,1]
	v_pk_fma_f32 v[30:31], v[0:1], v[30:31], v[170:171] op_sel_hi:[0,1,1]
	v_pk_fma_f32 v[58:59], v[0:1], v[112:113], v[172:173] op_sel_hi:[0,1,1]
	v_pk_fma_f32 v[34:35], v[0:1], v[34:35], v[174:175] op_sel_hi:[0,1,1]
	v_pk_fma_f32 v[38:39], v[0:1], v[38:39], v[176:177] op_sel_hi:[0,1,1]
	v_pk_fma_f32 v[60:61], v[0:1], v[128:129], v[178:179] op_sel_hi:[0,1,1]
	s_nop 0
	v_mov_b32_e32 v48, v16
	v_mov_b32_e32 v49, v12
	s_mul_i32 s78, s2, 0xc00
	s_or_b32 s2, s8, 12
	v_mov_b32_e32 v12, v17
	s_waitcnt vmcnt(5)
	v_mov_b32_e32 v0, v235
	v_pk_fma_f32 v[6:7], v[0:1], v[48:49], v[6:7] op_sel_hi:[0,1,1]
	v_mov_b32_e32 v48, v24
	v_mov_b32_e32 v49, v20
	v_pk_fma_f32 v[48:49], v[0:1], v[48:49], v[10:11] op_sel_hi:[0,1,1]
	v_mov_b32_e32 v10, v62
	v_mov_b32_e32 v11, v28
	v_pk_fma_f32 v[14:15], v[0:1], v[10:11], v[14:15] op_sel_hi:[0,1,1]
	v_mov_b32_e32 v10, v70
	v_mov_b32_e32 v11, v66
	v_pk_fma_f32 v[64:65], v[0:1], v[10:11], v[18:19] op_sel_hi:[0,1,1]
	v_mov_b32_e32 v10, v78
	v_mov_b32_e32 v11, v74
	v_pk_fma_f32 v[22:23], v[0:1], v[10:11], v[22:23] op_sel_hi:[0,1,1]
	v_mov_b32_e32 v10, v82
	v_mov_b32_e32 v11, v54
	v_pk_fma_f32 v[26:27], v[0:1], v[10:11], v[26:27] op_sel_hi:[0,1,1]
	v_mov_b32_e32 v10, v90
	v_mov_b32_e32 v11, v86
	v_pk_fma_f32 v[50:51], v[0:1], v[10:11], v[50:51] op_sel_hi:[0,1,1]
	v_mov_b32_e32 v10, v98
	v_mov_b32_e32 v11, v94
	v_pk_fma_f32 v[52:53], v[0:1], v[10:11], v[52:53] op_sel_hi:[0,1,1]
	v_mov_b32_e32 v10, v106
	v_mov_b32_e32 v11, v102
	v_pk_fma_f32 v[56:57], v[0:1], v[10:11], v[56:57] op_sel_hi:[0,1,1]
	v_mov_b32_e32 v10, v110
	v_mov_b32_e32 v11, v32
	v_pk_fma_f32 v[30:31], v[0:1], v[10:11], v[30:31] op_sel_hi:[0,1,1]
	v_mov_b32_e32 v10, v118
	v_mov_b32_e32 v11, v114
	v_pk_fma_f32 v[58:59], v[0:1], v[10:11], v[58:59] op_sel_hi:[0,1,1]
	v_mov_b32_e32 v10, v122
	v_mov_b32_e32 v11, v36
	v_pk_fma_f32 v[68:69], v[0:1], v[10:11], v[34:35] op_sel_hi:[0,1,1]
	v_mov_b32_e32 v10, v126
	v_mov_b32_e32 v11, v40
	v_pk_fma_f32 v[38:39], v[0:1], v[10:11], v[38:39] op_sel_hi:[0,1,1]
	v_mov_b32_e32 v10, v134
	v_mov_b32_e32 v11, v130
	v_pk_fma_f32 v[60:61], v[0:1], v[10:11], v[60:61] op_sel_hi:[0,1,1]
	v_mov_b32_e32 v10, v138
	v_mov_b32_e32 v11, v44
	v_pk_fma_f32 v[72:73], v[0:1], v[10:11], v[42:43] op_sel_hi:[0,1,1]
	v_mov_b32_e32 v10, v158
	v_mov_b32_e32 v11, v154
	v_pk_fma_f32 v[76:77], v[0:1], v[10:11], v[46:47] op_sel_hi:[0,1,1]
	v_lshl_add_u64 v[10:11], s[78:79], 2, v[150:151]
	v_fmac_f32_e32 v191, v0, v8
	s_nop 0
	s_mul_i32 s78, s2, 0xc00
	v_mov_b32_e32 v20, v25
	v_mov_b32_e32 v28, v63
	v_mov_b32_e32 v66, v71
	v_mov_b32_e32 v74, v79
	v_mov_b32_e32 v54, v83
	v_mov_b32_e32 v86, v91
	v_mov_b32_e32 v94, v99
	v_mov_b32_e32 v102, v107
	v_mov_b32_e32 v32, v111
	v_mov_b32_e32 v114, v119
	v_mov_b32_e32 v36, v123
	v_mov_b32_e32 v40, v127
	v_mov_b32_e32 v130, v135
	v_mov_b32_e32 v44, v139
	v_mov_b32_e32 v154, v159
	s_or_b32 s2, s8, 13
	s_waitcnt vmcnt(4)
; DI void prep_mod_item(const Params& p, int item, float* smem) {
;     ...
; #pragma unroll 16
;     for (int kk = 0; kk < 64; ++kk) {
;       const float w = Wh[(size_t)kk * 3072];
; #pragma unroll
;       for (int b = 0; b < 33; ++b) acc[b] += sg[b * 512 + kk] * w;
;     }
	v_mov_b32_e32 v0, v236
	v_pk_fma_f32 v[10:11], v[0:1], v[12:13], v[6:7] op_sel_hi:[0,1,1]
	v_lshl_add_u64 v[6:7], s[78:79], 2, v[150:151]
	v_fmac_f32_e32 v191, v0, v9
	v_pk_fma_f32 v[20:21], v[0:1], v[20:21], v[48:49] op_sel_hi:[0,1,1]
	v_pk_fma_f32 v[18:19], v[0:1], v[28:29], v[14:15] op_sel_hi:[0,1,1]
	v_pk_fma_f32 v[34:35], v[0:1], v[66:67], v[64:65] op_sel_hi:[0,1,1]
	v_pk_fma_f32 v[42:43], v[0:1], v[74:75], v[22:23] op_sel_hi:[0,1,1]
	v_pk_fma_f32 v[48:49], v[0:1], v[54:55], v[26:27] op_sel_hi:[0,1,1]
	v_pk_fma_f32 v[46:47], v[0:1], v[86:87], v[50:51] op_sel_hi:[0,1,1]
	v_pk_fma_f32 v[66:67], v[0:1], v[94:95], v[52:53] op_sel_hi:[0,1,1]
	v_pk_fma_f32 v[70:71], v[0:1], v[102:103], v[56:57] op_sel_hi:[0,1,1]
	v_pk_fma_f32 v[78:79], v[0:1], v[32:33], v[30:31] op_sel_hi:[0,1,1]
	v_pk_fma_f32 v[90:91], v[0:1], v[114:115], v[58:59] op_sel_hi:[0,1,1]
	v_pk_fma_f32 v[84:85], v[0:1], v[36:37], v[68:69] op_sel_hi:[0,1,1]
	v_pk_fma_f32 v[82:83], v[0:1], v[40:41], v[38:39] op_sel_hi:[0,1,1]
	v_pk_fma_f32 v[116:117], v[0:1], v[130:131], v[60:61] op_sel_hi:[0,1,1]
	v_pk_fma_f32 v[114:115], v[0:1], v[44:45], v[72:73] op_sel_hi:[0,1,1]
	v_pk_fma_f32 v[134:135], v[0:1], v[154:155], v[76:77] op_sel_hi:[0,1,1]
	s_nop 0
	ds_read_b128 v[6:9], v195 offset:2096
	ds_read_b128 v[14:17], v195 offset:4144
	s_mul_i32 s78, s2, 0xc00
	s_or_b32 s2, s8, 14
	s_waitcnt lgkmcnt(1)
	v_mov_b32_e32 v13, v6
	s_waitcnt lgkmcnt(0)
	v_mov_b32_e32 v12, v14
	v_mov_b32_e32 v6, v15
	s_waitcnt vmcnt(3)
	v_mov_b32_e32 v0, v237
	v_pk_fma_f32 v[136:137], v[0:1], v[12:13], v[10:11] op_sel_hi:[0,1,1]
	ds_read_b128 v[10:13], v195 offset:6192
	ds_read_b128 v[22:25], v195 offset:8240
	v_fmac_f32_e32 v191, v0, v2
	v_add_u32_e32 v2, 0x10030, v195
	s_waitcnt lgkmcnt(1)
	v_mov_b32_e32 v27, v10
	s_waitcnt lgkmcnt(0)
	v_mov_b32_e32 v26, v22
	v_pk_fma_f32 v[138:139], v[0:1], v[26:27], v[20:21] op_sel_hi:[0,1,1]
	ds_read_b128 v[26:29], v195 offset:10288
	ds_read_b128 v[30:33], v195 offset:12336
	v_mov_b32_e32 v10, v23
	s_waitcnt lgkmcnt(1)
	v_mov_b32_e32 v21, v26
	s_waitcnt lgkmcnt(0)
	v_mov_b32_e32 v20, v30
	v_pk_fma_f32 v[140:141], v[0:1], v[20:21], v[18:19] op_sel_hi:[0,1,1]
	ds_read_b128 v[18:21], v195 offset:14384
	ds_read_b128 v[38:41], v195 offset:16432
	v_mov_b32_e32 v26, v31
	s_waitcnt lgkmcnt(1)
	v_mov_b32_e32 v37, v18
	s_waitcnt lgkmcnt(0)
	v_mov_b32_e32 v36, v38
	v_pk_fma_f32 v[152:153], v[0:1], v[36:37], v[34:35] op_sel_hi:[0,1,1]
	ds_read_b128 v[34:37], v195 offset:18480
	ds_read_b128 v[54:57], v195 offset:20528
	v_mov_b32_e32 v18, v39
	s_waitcnt lgkmcnt(1)
	v_mov_b32_e32 v45, v34
	s_waitcnt lgkmcnt(0)
	v_mov_b32_e32 v44, v54
	v_pk_fma_f32 v[154:155], v[0:1], v[44:45], v[42:43] op_sel_hi:[0,1,1]
	ds_read_b128 v[42:45], v195 offset:22576
	ds_read_b128 v[58:61], v195 offset:24624
	v_mov_b32_e32 v34, v55
	s_waitcnt lgkmcnt(1)
	v_mov_b32_e32 v51, v42
	s_waitcnt lgkmcnt(0)
	v_mov_b32_e32 v50, v58
	v_pk_fma_f32 v[156:157], v[0:1], v[50:51], v[48:49] op_sel_hi:[0,1,1]
	ds_read_b128 v[50:53], v195 offset:26672
	ds_read_b128 v[62:65], v195 offset:28720
	v_mov_b32_e32 v42, v59
	s_waitcnt lgkmcnt(1)
	v_mov_b32_e32 v49, v50
	s_waitcnt lgkmcnt(0)
	v_mov_b32_e32 v48, v62
	v_pk_fma_f32 v[158:159], v[0:1], v[48:49], v[46:47] op_sel_hi:[0,1,1]
	ds_read_b128 v[46:49], v195 offset:30768
	ds_read_b128 v[74:77], v195 offset:32816
	v_mov_b32_e32 v50, v63
	s_waitcnt lgkmcnt(1)
	v_mov_b32_e32 v69, v46
	s_waitcnt lgkmcnt(0)
	v_mov_b32_e32 v68, v74
	v_pk_fma_f32 v[160:161], v[0:1], v[68:69], v[66:67] op_sel_hi:[0,1,1]
	ds_read_b128 v[66:69], v195 offset:34864
	ds_read_b128 v[86:89], v195 offset:36912
	v_mov_b32_e32 v46, v75
	s_waitcnt lgkmcnt(1)
	v_mov_b32_e32 v73, v66
	s_waitcnt lgkmcnt(0)
	v_mov_b32_e32 v72, v86
	v_pk_fma_f32 v[162:163], v[0:1], v[72:73], v[70:71] op_sel_hi:[0,1,1]
	ds_read_b128 v[70:73], v195 offset:38960
	ds_read_b128 v[98:101], v195 offset:41008
	v_mov_b32_e32 v66, v87
	s_waitcnt lgkmcnt(1)
	v_mov_b32_e32 v81, v70
	s_waitcnt lgkmcnt(0)
	v_mov_b32_e32 v80, v98
	v_pk_fma_f32 v[164:165], v[0:1], v[80:81], v[78:79] op_sel_hi:[0,1,1]
	ds_read_b128 v[78:81], v195 offset:43056
	ds_read_b128 v[110:113], v195 offset:45104
	ds_read_b128 v[94:97], v195 offset:47152
	ds_read_b128 v[106:109], v195 offset:49200
	v_mov_b32_e32 v70, v99
	s_waitcnt lgkmcnt(3)
	v_mov_b32_e32 v93, v78
	s_waitcnt lgkmcnt(2)
	v_mov_b32_e32 v92, v110
	v_pk_fma_f32 v[166:167], v[0:1], v[92:93], v[90:91] op_sel_hi:[0,1,1]
	s_waitcnt lgkmcnt(0)
	v_mov_b32_e32 v90, v106
	v_mov_b32_e32 v91, v94
	v_pk_fma_f32 v[168:169], v[0:1], v[90:91], v[84:85] op_sel_hi:[0,1,1]
	ds_read_b128 v[90:93], v195 offset:51248
	ds_read_b128 v[102:105], v195 offset:53296
	v_mov_b32_e32 v78, v111
	v_mov_b32_e32 v94, v107
	s_waitcnt lgkmcnt(1)
	v_mov_b32_e32 v85, v90
	s_waitcnt lgkmcnt(0)
	v_mov_b32_e32 v84, v102
	v_pk_fma_f32 v[170:171], v[0:1], v[84:85], v[82:83] op_sel_hi:[0,1,1]
	ds_read_b128 v[82:85], v195 offset:55344
	ds_read_b128 v[126:129], v195 offset:57392
	ds_read_b128 v[122:125], v195 offset:59440
	ds_read_b128 v[130:133], v195 offset:61488
	v_mov_b32_e32 v90, v103
	s_waitcnt lgkmcnt(3)
	v_mov_b32_e32 v119, v82
	s_waitcnt lgkmcnt(2)
	v_mov_b32_e32 v118, v126
	v_pk_fma_f32 v[172:173], v[0:1], v[118:119], v[116:117] op_sel_hi:[0,1,1]
	s_waitcnt lgkmcnt(0)
	v_mov_b32_e32 v116, v130
	v_mov_b32_e32 v117, v122
	v_pk_fma_f32 v[174:175], v[0:1], v[116:117], v[114:115] op_sel_hi:[0,1,1]
	ds_read_b128 v[114:117], v195 offset:63536
	ds_read_b128 v[118:121], v2
	v_mov_b32_e32 v82, v127
	v_mov_b32_e32 v122, v131
	s_waitcnt lgkmcnt(1)
	v_mov_b32_e32 v177, v114
	s_waitcnt lgkmcnt(0)
; DI void prep_mod_item(const Params& p, int item, float* smem) {
;     ...
; #pragma unroll 16
;     for (int kk = 0; kk < 64; ++kk) {
;       const float w = Wh[(size_t)kk * 3072];
; #pragma unroll
;       for (int b = 0; b < 33; ++b) acc[b] += sg[b * 512 + kk] * w;
;     }
;   }
;   __syncthreads();
; #pragma unroll
;   for (int b = 0; b < 33; ++b) smem[(wv * 33 + b) * 64 + lane] = acc[b];
;   __syncthreads();
;   for (int e = tid; e < 33 * 64; e += NTHR) {
;     const int l = e & 63, b = e >> 6;
;     float s = 0.f;
; #pragma unroll
;     for (int w = 0; w < 8; ++w) s += smem[(w * 33 + b) * 64 + l];
;     const int cc = cgp * 64 + l;
;     p.mod[((size_t)layer * 33 + b) * 3072 + cc] = s + p.b_ada[layer * 3072 + cc];
	v_mov_b32_e32 v176, v118
	v_pk_fma_f32 v[134:135], v[0:1], v[176:177], v[134:135] op_sel_hi:[0,1,1]
	v_lshl_add_u64 v[176:177], s[78:79], 2, v[150:151]
	s_nop 0
	s_mul_i32 s78, s2, 0xc00
	v_mov_b32_e32 v114, v119
	v_lshl_add_u64 v[14:15], s[78:79], 2, v[150:151]
	s_or_b32 s2, s8, 15
	s_mul_i32 s78, s2, 0xc00
	s_add_i32 s8, s8, 16
	s_cmp_eq_u32 s8, 64
	s_waitcnt vmcnt(2)
	v_mov_b32_e32 v0, v238
	v_fmac_f32_e32 v191, v0, v3
	v_pk_fma_f32 v[2:3], v[0:1], v[6:7], v[136:137] op_sel_hi:[0,1,1]
	v_pk_fma_f32 v[6:7], v[0:1], v[10:11], v[138:139] op_sel_hi:[0,1,1]
	v_pk_fma_f32 v[10:11], v[0:1], v[26:27], v[140:141] op_sel_hi:[0,1,1]
	v_pk_fma_f32 v[22:23], v[0:1], v[18:19], v[152:153] op_sel_hi:[0,1,1]
	v_pk_fma_f32 v[26:27], v[0:1], v[34:35], v[154:155] op_sel_hi:[0,1,1]
	v_pk_fma_f32 v[30:31], v[0:1], v[42:43], v[156:157] op_sel_hi:[0,1,1]
	v_pk_fma_f32 v[34:35], v[0:1], v[50:51], v[158:159] op_sel_hi:[0,1,1]
	v_pk_fma_f32 v[38:39], v[0:1], v[46:47], v[160:161] op_sel_hi:[0,1,1]
	v_pk_fma_f32 v[42:43], v[0:1], v[66:67], v[162:163] op_sel_hi:[0,1,1]
	v_pk_fma_f32 v[46:47], v[0:1], v[70:71], v[164:165] op_sel_hi:[0,1,1]
	v_pk_fma_f32 v[66:67], v[0:1], v[78:79], v[166:167] op_sel_hi:[0,1,1]
	v_pk_fma_f32 v[70:71], v[0:1], v[94:95], v[168:169] op_sel_hi:[0,1,1]
	v_pk_fma_f32 v[74:75], v[0:1], v[90:91], v[170:171] op_sel_hi:[0,1,1]
	v_pk_fma_f32 v[78:79], v[0:1], v[82:83], v[172:173] op_sel_hi:[0,1,1]
	v_pk_fma_f32 v[82:83], v[0:1], v[122:123], v[174:175] op_sel_hi:[0,1,1]
	v_pk_fma_f32 v[86:87], v[0:1], v[114:115], v[134:135] op_sel_hi:[0,1,1]
	s_nop 0
	v_mov_b32_e32 v14, v16
	v_mov_b32_e32 v15, v8
	v_mov_b32_e32 v8, v17
	s_waitcnt vmcnt(1)
	v_mov_b32_e32 v0, v239
	v_pk_fma_f32 v[14:15], v[0:1], v[14:15], v[2:3] op_sel_hi:[0,1,1]
	v_mov_b32_e32 v2, v24
	v_mov_b32_e32 v3, v12
	v_pk_fma_f32 v[62:63], v[0:1], v[2:3], v[6:7] op_sel_hi:[0,1,1]
	v_mov_b32_e32 v2, v32
	v_mov_b32_e32 v3, v28
	v_pk_fma_f32 v[18:19], v[0:1], v[2:3], v[10:11] op_sel_hi:[0,1,1]
	v_mov_b32_e32 v2, v40
	v_mov_b32_e32 v3, v20
	v_pk_fma_f32 v[58:59], v[0:1], v[2:3], v[22:23] op_sel_hi:[0,1,1]
	v_mov_b32_e32 v2, v56
	v_mov_b32_e32 v3, v36
	v_pk_fma_f32 v[22:23], v[0:1], v[2:3], v[26:27] op_sel_hi:[0,1,1]
	v_mov_b32_e32 v2, v60
	v_mov_b32_e32 v3, v44
	v_pk_fma_f32 v[26:27], v[0:1], v[2:3], v[30:31] op_sel_hi:[0,1,1]
	v_mov_b32_e32 v2, v64
	v_mov_b32_e32 v3, v52
	v_pk_fma_f32 v[30:31], v[0:1], v[2:3], v[34:35] op_sel_hi:[0,1,1]
	v_mov_b32_e32 v2, v76
	v_mov_b32_e32 v3, v48
	v_pk_fma_f32 v[54:55], v[0:1], v[2:3], v[38:39] op_sel_hi:[0,1,1]
	v_mov_b32_e32 v2, v88
	v_mov_b32_e32 v3, v68
	v_pk_fma_f32 v[50:51], v[0:1], v[2:3], v[42:43] op_sel_hi:[0,1,1]
	v_mov_b32_e32 v2, v100
	v_mov_b32_e32 v3, v72
	v_pk_fma_f32 v[46:47], v[0:1], v[2:3], v[46:47] op_sel_hi:[0,1,1]
	v_mov_b32_e32 v2, v112
	v_mov_b32_e32 v3, v80
	v_pk_fma_f32 v[34:35], v[0:1], v[2:3], v[66:67] op_sel_hi:[0,1,1]
	v_mov_b32_e32 v2, v108
	v_mov_b32_e32 v3, v96
	v_pk_fma_f32 v[42:43], v[0:1], v[2:3], v[70:71] op_sel_hi:[0,1,1]
	v_mov_b32_e32 v2, v104
	v_mov_b32_e32 v3, v92
	v_pk_fma_f32 v[38:39], v[0:1], v[2:3], v[74:75] op_sel_hi:[0,1,1]
	v_mov_b32_e32 v2, v128
	v_mov_b32_e32 v3, v84
	v_pk_fma_f32 v[10:11], v[0:1], v[2:3], v[78:79] op_sel_hi:[0,1,1]
	v_mov_b32_e32 v2, v132
	v_mov_b32_e32 v3, v124
	v_pk_fma_f32 v[6:7], v[0:1], v[2:3], v[82:83] op_sel_hi:[0,1,1]
	v_mov_b32_e32 v2, v120
	v_mov_b32_e32 v3, v116
	v_lshl_add_u64 v[66:67], s[78:79], 2, v[150:151]
	v_fmac_f32_e32 v191, v0, v4
	v_pk_fma_f32 v[2:3], v[0:1], v[2:3], v[86:87] op_sel_hi:[0,1,1]
	s_nop 0
	v_mov_b32_e32 v12, v25
	v_mov_b32_e32 v28, v33
	v_mov_b32_e32 v20, v41
	v_mov_b32_e32 v36, v57
	v_mov_b32_e32 v44, v61
	v_mov_b32_e32 v52, v65
	v_mov_b32_e32 v48, v77
	v_mov_b32_e32 v68, v89
	v_mov_b32_e32 v72, v101
	v_mov_b32_e32 v80, v113
	v_mov_b32_e32 v96, v109
	v_mov_b32_e32 v92, v105
	v_mov_b32_e32 v84, v129
	v_mov_b32_e32 v124, v133
	v_mov_b32_e32 v116, v121
	s_waitcnt vmcnt(0)
	v_mov_b32_e32 v0, v240
	v_fmac_f32_e32 v191, v0, v5
	v_pk_fma_f32 v[14:15], v[0:1], v[8:9], v[14:15] op_sel_hi:[0,1,1]
	v_pk_fma_f32 v[16:17], v[0:1], v[12:13], v[62:63] op_sel_hi:[0,1,1]
	v_pk_fma_f32 v[18:19], v[0:1], v[28:29], v[18:19] op_sel_hi:[0,1,1]
	v_pk_fma_f32 v[20:21], v[0:1], v[20:21], v[58:59] op_sel_hi:[0,1,1]
	v_pk_fma_f32 v[22:23], v[0:1], v[36:37], v[22:23] op_sel_hi:[0,1,1]
	v_pk_fma_f32 v[26:27], v[0:1], v[44:45], v[26:27] op_sel_hi:[0,1,1]
	v_pk_fma_f32 v[30:31], v[0:1], v[52:53], v[30:31] op_sel_hi:[0,1,1]
	v_pk_fma_f32 v[24:25], v[0:1], v[48:49], v[54:55] op_sel_hi:[0,1,1]
	v_pk_fma_f32 v[28:29], v[0:1], v[68:69], v[50:51] op_sel_hi:[0,1,1]
	v_pk_fma_f32 v[32:33], v[0:1], v[72:73], v[46:47] op_sel_hi:[0,1,1]
	v_pk_fma_f32 v[34:35], v[0:1], v[80:81], v[34:35] op_sel_hi:[0,1,1]
	v_pk_fma_f32 v[36:37], v[0:1], v[96:97], v[42:43] op_sel_hi:[0,1,1]
	v_pk_fma_f32 v[38:39], v[0:1], v[92:93], v[38:39] op_sel_hi:[0,1,1]
	v_pk_fma_f32 v[40:41], v[0:1], v[84:85], v[10:11] op_sel_hi:[0,1,1]
	v_pk_fma_f32 v[42:43], v[0:1], v[124:125], v[6:7] op_sel_hi:[0,1,1]
	v_pk_fma_f32 v[44:45], v[0:1], v[116:117], v[2:3] op_sel_hi:[0,1,1]
	s_cbranch_scc0 .LBB0_67
	s_movk_i32 s2, 0x200
	s_mov_b64 s[8:9], 0
	s_and_b64 vcc, exec, s[0:1]
	s_cbranch_vccz .LBB0_63
	v_lshrrev_b32_e32 v0, 6, v188
	v_lshl_add_u32 v2, v189, 2, 0
	s_movk_i32 s0, 0x2100
	v_mad_u64_u32 v[4:5], s[0:1], v0, s0, v[2:3]
	s_movk_i32 s0, 0x840
	s_nop 0
	v_cmp_gt_i32_e32 vcc, s0, v188
	s_barrier
	ds_write2st64_b32 v4, v191, v15 offset1:1
	ds_write2st64_b32 v4, v14, v17 offset0:2 offset1:3
	ds_write2st64_b32 v4, v16, v19 offset0:4 offset1:5
	ds_write2st64_b32 v4, v18, v21 offset0:6 offset1:7
	ds_write2st64_b32 v4, v20, v23 offset0:8 offset1:9
	ds_write2st64_b32 v4, v22, v27 offset0:10 offset1:11
	ds_write2st64_b32 v4, v26, v31 offset0:12 offset1:13
	ds_write2st64_b32 v4, v30, v25 offset0:14 offset1:15
	ds_write2st64_b32 v4, v24, v29 offset0:16 offset1:17
	ds_write2st64_b32 v4, v28, v33 offset0:18 offset1:19
	ds_write2st64_b32 v4, v32, v35 offset0:20 offset1:21
	ds_write2st64_b32 v4, v34, v37 offset0:22 offset1:23
	ds_write2st64_b32 v4, v36, v39 offset0:24 offset1:25
	ds_write2st64_b32 v4, v38, v41 offset0:26 offset1:27
	ds_write2st64_b32 v4, v40, v43 offset0:28 offset1:29
	ds_write2st64_b32 v4, v42, v45 offset0:30 offset1:31
	ds_write_b32 v4, v44 offset:8192
	s_waitcnt lgkmcnt(0)
	s_barrier
	s_and_saveexec_b64 s[0:1], vcc
	s_cbranch_execz .LBB0_72
	s_and_b32 s2, 0xffff, s12
	s_mul_i32 s6, s2, 0xc00
	v_add_lshl_u32 v0, v142, s6, 2
	v_lshl_add_u64 v[4:5], s[62:63], 0, v[0:1]
	v_lshlrev_b32_e32 v0, 2, v142
	s_mul_i32 s2, s12, 33
	v_lshl_add_u64 v[6:7], s[50:51], 0, v[0:1]
	s_mov_b64 s[6:7], 0
